# attn loop: leaner vote tail (cross-half max only on rare path), vmcnt(3) staging wait, no swaps, pk_add sums
# speedup vs baseline: 1.0482x; 1.0089x over previous
; #define LAS __attribute__((address_space(3)))
; __device__ __forceinline__ void qkt(f32x16& p0, f32x16& p1, const LAS unsigned char* Ks, const bf16x8* qr, const f32x16& negm, int r32, int hi) {
;   bf16x8 kf[12];
; #pragma unroll
;   for (int d0 = 0; d0 < 6; ++d0) { const int cb = (d0 * 16 + hi * 8) * 2;
;     kf[2 * d0] = *(const LAS bf16x8*)(Ks + KSWZ(r32, cb)); kf[2 * d0 + 1] = *(const LAS bf16x8*)(Ks + KSWZ(32 + r32, cb)); }
;   SBAR();
;   p0 = __builtin_amdgcn_mfma_f32_32x32x16_bf16(kf[0], qr[0], negm, 0, 0, 0); p1 = __builtin_amdgcn_mfma_f32_32x32x16_bf16(kf[1], qr[0], negm, 0, 0, 0);
; #pragma unroll
;   for (int d0 = 1; d0 < 6; ++d0) { p0 = __builtin_amdgcn_mfma_f32_32x32x16_bf16(kf[2 * d0], qr[d0], p0, 0, 0, 0); p1 = __builtin_amdgcn_mfma_f32_32x32x16_bf16(kf[2 * d0 + 1], qr[d0], p1, 0, 0, 0); }
; }
; __device__ __forceinline__ int v_st(int k, int c) { const int kk = (k & ~0xC) | ((k & 4) << 1) | ((k & 8) >> 1); return ((kk >> 3) * 4 + (c >> 5)) * 512 + ((kk & 7) * 32 + (c & 31)) * 2; }
; __device__ __forceinline__ int v_rd_base(int lane) { return ((lane & 3) << 3) | (((lane >> 2) & 3) << 6) | (((lane >> 4) & 1) << 5) | (((lane >> 5) & 1) << 8); }
; template <int OFF> __device__ __forceinline__ s16x4 tr_read(int vb) {
;   s16x4 r; asm volatile("ds_read_b64_tr_b16 %0, %1 offset:%2" : "=&v"(r) : "v"(vb), "i"(OFF) : "memory"); return r;
; }
; __device__ __forceinline__ void pv_d0(f32x16* o, int vb, bf16x8 pa0, bf16x8 pa1, bf16x8 pa2, bf16x8 pa3) {
;   const s16x4 a0 = tr_read<v_rd_off(0, 0, 0)>(vb), b0 = tr_read<v_rd_off(0, 0, 1)>(vb), a1 = tr_read<v_rd_off(0, 1, 0)>(vb), b1 = tr_read<v_rd_off(0, 1, 1)>(vb);
;   const s16x4 a2 = tr_read<v_rd_off(0, 2, 0)>(vb), b2 = tr_read<v_rd_off(0, 2, 1)>(vb), a3 = tr_read<v_rd_off(0, 3, 0)>(vb), b3 = tr_read<v_rd_off(0, 3, 1)>(vb);
;   const s16x4 c0 = tr_read<v_rd_off(1, 0, 0)>(vb), d0 = tr_read<v_rd_off(1, 0, 1)>(vb), c1 = tr_read<v_rd_off(1, 1, 0)>(vb), d1 = tr_read<v_rd_off(1, 1, 1)>(vb);
;   const s16x4 c2 = tr_read<v_rd_off(1, 2, 0)>(vb), d2 = tr_read<v_rd_off(1, 2, 1)>(vb), c3 = tr_read<v_rd_off(1, 3, 0)>(vb), d3 = tr_read<v_rd_off(1, 3, 1)>(vb);
;   asm volatile("s_waitcnt lgkmcnt(0)" ::: "memory"); SBAR();
;     ...
;   o[0] = __builtin_amdgcn_mfma_f32_32x32x16_bf16(pa0, PK(a0, b0), o[0], 0, 0, 0); o[1] = __builtin_amdgcn_mfma_f32_32x32x16_bf16(pa0, PK(c0, d0), o[1], 0, 0, 0);
.Lmy_attn_m1:
	ds_read_b64_tr_b16 v[70:71], v174 offset:0x1000
	ds_read_b64_tr_b16 v[72:73], v174 offset:0x1800
	ds_read_b64_tr_b16 v[162:163], v174 offset:0x1200
	ds_read_b64_tr_b16 v[164:165], v174 offset:0x1a00
	ds_read_b64_tr_b16 v[74:75], v174 offset:0x2000
	ds_read_b64_tr_b16 v[76:77], v174 offset:0x2800
	ds_read_b64_tr_b16 v[166:167], v174 offset:0x2200
	ds_read_b64_tr_b16 v[168:169], v174 offset:0x2a00
	ds_read_b64_tr_b16 v[78:79], v174 offset:0x3000
	ds_read_b64_tr_b16 v[80:81], v174 offset:0x3800
	ds_read_b64_tr_b16 v[170:171], v174 offset:0x3200
	ds_read_b64_tr_b16 v[172:173], v174 offset:0x3a00
	s_waitcnt lgkmcnt(14)
	v_mfma_f32_32x32x16_bf16 v[34:49], v[62:65], v[66:69], v[34:49]
	s_waitcnt lgkmcnt(12)
	v_mfma_f32_32x32x16_bf16 v[18:33], v[62:65], v[158:161], v[18:33]
	s_waitcnt lgkmcnt(10)
	v_mfma_f32_32x32x16_bf16 v[34:49], v[50:53], v[70:73], v[34:49]
	s_waitcnt lgkmcnt(8)
	v_mfma_f32_32x32x16_bf16 v[18:33], v[50:53], v[162:165], v[18:33]
	s_waitcnt lgkmcnt(6)
	v_mfma_f32_32x32x16_bf16 v[34:49], v[54:57], v[74:77], v[34:49]
	s_waitcnt lgkmcnt(4)
	v_mfma_f32_32x32x16_bf16 v[18:33], v[54:57], v[166:169], v[18:33]
	v_add_u32_e32 v54, s5, v146
	v_add_u32_e32 v55, v54, v147
	ds_read_b128 v[50:53], v55 offset:49152
	ds_read_b128 v[158:161], v55 offset:57344
	v_add_u32_e32 v55, v54, v148
	ds_read_b128 v[162:165], v55 offset:49152
	ds_read_b128 v[166:169], v55 offset:57344
	v_add_u32_e32 v55, v54, v149
	s_waitcnt lgkmcnt(6)
	v_mfma_f32_32x32x16_bf16 v[34:49], v[58:61], v[78:81], v[34:49]
	s_waitcnt lgkmcnt(4)
	v_mfma_f32_32x32x16_bf16 v[18:33], v[58:61], v[170:173], v[18:33]
	ds_read_b128 v[170:173], v55 offset:49152
	ds_read_b128 v[178:181], v55 offset:57344
	v_add_u32_e32 v55, v54, v150
	ds_read_b128 v[182:185], v55 offset:49152
	ds_read_b128 v[186:189], v55 offset:57344
	v_add_u32_e32 v55, v54, v151
	v_add_u32_e32 v54, v54, v152
	ds_read_b128 v[190:193], v55 offset:49152
	ds_read_b128 v[194:197], v55 offset:57344
	ds_read_b128 v[198:201], v54 offset:49152
	ds_read_b128 v[202:205], v54 offset:57344
	s_waitcnt lgkmcnt(11)
	v_mfma_f32_32x32x16_bf16 v[66:81], v[50:53], v[82:85], v[2:17]
	s_waitcnt lgkmcnt(9)
	v_mfma_f32_32x32x16_bf16 v[66:81], v[162:165], v[86:89], v[66:81]
	s_waitcnt lgkmcnt(7)
	v_mfma_f32_32x32x16_bf16 v[66:81], v[170:173], v[90:93], v[66:81]
	s_waitcnt lgkmcnt(5)
	v_mfma_f32_32x32x16_bf16 v[66:81], v[182:185], v[94:97], v[66:81]
	s_waitcnt lgkmcnt(3)
	v_mfma_f32_32x32x16_bf16 v[66:81], v[190:193], v[98:101], v[66:81]
	s_waitcnt lgkmcnt(1)
	v_mfma_f32_32x32x16_bf16 v[66:81], v[198:201], v[102:105], v[66:81]
	s_waitcnt lgkmcnt(0)
	v_mfma_f32_32x32x16_bf16 v[50:65], v[158:161], v[82:85], v[2:17]
	v_mfma_f32_32x32x16_bf16 v[50:65], v[166:169], v[86:89], v[50:65]
	v_mfma_f32_32x32x16_bf16 v[50:65], v[178:181], v[90:93], v[50:65]
	v_mfma_f32_32x32x16_bf16 v[50:65], v[186:189], v[94:97], v[50:65]
	v_mfma_f32_32x32x16_bf16 v[50:65], v[194:197], v[98:101], v[50:65]
	v_mfma_f32_32x32x16_bf16 v[50:65], v[202:205], v[102:105], v[50:65]
	s_setprio 0
	v_max3_f32 v158, v66, v67, v68
	v_max3_f32 v159, v69, v70, v71
	v_max3_f32 v158, v158, v72, v73
	v_max3_f32 v159, v159, v74, v75
	v_max3_f32 v158, v158, v76, v77
	v_max3_f32 v159, v159, v78, v79
	v_max3_f32 v158, v158, v80, v81
	s_nop 3
	v_max3_f32 v159, v159, v50, v51
	v_max3_f32 v158, v158, v52, v53
	v_max3_f32 v159, v159, v54, v55
	v_max3_f32 v158, v158, v56, v57
	v_max3_f32 v159, v159, v58, v59
	v_max3_f32 v158, v158, v60, v61
	v_max3_f32 v159, v159, v62, v63
	v_max3_f32 v158, v158, v64, v65
	v_max_f32_e32 v159, v158, v159
	v_cmp_ge_f32_e32 vcc, s93, v159
	s_cmp_eq_u64 vcc, exec
	v_mov_b32_e32 v158, 1.0
	s_barrier
	s_cbranch_scc0 .LBB0_540

; #define LAS __attribute__((address_space(3)))
; __device__ __forceinline__ void qkt(f32x16& p0, f32x16& p1, const LAS unsigned char* Ks, const bf16x8* qr, const f32x16& negm, int r32, int hi) {
;   bf16x8 kf[12];
; #pragma unroll
;   for (int d0 = 0; d0 < 6; ++d0) { const int cb = (d0 * 16 + hi * 8) * 2;
;     kf[2 * d0] = *(const LAS bf16x8*)(Ks + KSWZ(r32, cb)); kf[2 * d0 + 1] = *(const LAS bf16x8*)(Ks + KSWZ(32 + r32, cb)); }
;   SBAR();
;   p0 = __builtin_amdgcn_mfma_f32_32x32x16_bf16(kf[0], qr[0], negm, 0, 0, 0); p1 = __builtin_amdgcn_mfma_f32_32x32x16_bf16(kf[1], qr[0], negm, 0, 0, 0);
; #pragma unroll
;   for (int d0 = 1; d0 < 6; ++d0) { p0 = __builtin_amdgcn_mfma_f32_32x32x16_bf16(kf[2 * d0], qr[d0], p0, 0, 0, 0); p1 = __builtin_amdgcn_mfma_f32_32x32x16_bf16(kf[2 * d0 + 1], qr[d0], p1, 0, 0, 0); }
; }
; __device__ __forceinline__ int v_st(int k, int c) { const int kk = (k & ~0xC) | ((k & 4) << 1) | ((k & 8) >> 1); return ((kk >> 3) * 4 + (c >> 5)) * 512 + ((kk & 7) * 32 + (c & 31)) * 2; }
; __device__ __forceinline__ int v_rd_base(int lane) { return ((lane & 3) << 3) | (((lane >> 2) & 3) << 6) | (((lane >> 4) & 1) << 5) | (((lane >> 5) & 1) << 8); }
; template <int OFF> __device__ __forceinline__ s16x4 tr_read(int vb) {
;   s16x4 r; asm volatile("ds_read_b64_tr_b16 %0, %1 offset:%2" : "=&v"(r) : "v"(vb), "i"(OFF) : "memory"); return r;
; }
; __device__ __forceinline__ void pv_d0(f32x16* o, int vb, bf16x8 pa0, bf16x8 pa1, bf16x8 pa2, bf16x8 pa3) {
;   const s16x4 a0 = tr_read<v_rd_off(0, 0, 0)>(vb), b0 = tr_read<v_rd_off(0, 0, 1)>(vb), a1 = tr_read<v_rd_off(0, 1, 0)>(vb), b1 = tr_read<v_rd_off(0, 1, 1)>(vb);
;   const s16x4 a2 = tr_read<v_rd_off(0, 2, 0)>(vb), b2 = tr_read<v_rd_off(0, 2, 1)>(vb), a3 = tr_read<v_rd_off(0, 3, 0)>(vb), b3 = tr_read<v_rd_off(0, 3, 1)>(vb);
;   const s16x4 c0 = tr_read<v_rd_off(1, 0, 0)>(vb), d0 = tr_read<v_rd_off(1, 0, 1)>(vb), c1 = tr_read<v_rd_off(1, 1, 0)>(vb), d1 = tr_read<v_rd_off(1, 1, 1)>(vb);
;   const s16x4 c2 = tr_read<v_rd_off(1, 2, 0)>(vb), d2 = tr_read<v_rd_off(1, 2, 1)>(vb), c3 = tr_read<v_rd_off(1, 3, 0)>(vb), d3 = tr_read<v_rd_off(1, 3, 1)>(vb);
;   asm volatile("s_waitcnt lgkmcnt(0)" ::: "memory"); SBAR();
;     ...
;   o[0] = __builtin_amdgcn_mfma_f32_32x32x16_bf16(pa0, PK(a0, b0), o[0], 0, 0, 0); o[1] = __builtin_amdgcn_mfma_f32_32x32x16_bf16(pa0, PK(c0, d0), o[1], 0, 0, 0);
.LBB0_529:
	s_add_i32 s23, s65, s11
	s_add_i32 s0, s23, 1
	s_cmpk_gt_u32 s0, 0x83
	s_cbranch_scc1 .LBB0_531
	s_and_b64 s[24:25], s[54:55], exec
	s_cselect_b32 s1, s22, s10
	s_min_u32 s0, s0, 0x81
	v_add_u32_e32 v158, s1, v131
	s_lshl_b32 s0, s0, 6
	s_waitcnt vmcnt(3)
	ds_write_b128 v158, v[106:109]
	v_add_u32_e32 v106, s1, v133
	s_add_i32 s0, s4, s0
	ds_write_b128 v106, v[110:113]
	v_add_u32_e32 v106, s1, v145
	s_ashr_i32 s1, s0, 31
	ds_write_b128 v106, v[114:117] offset:49152
	s_lshl_b64 s[100:101], s[0:1], 11
	v_lshl_add_u64 v[106:107], v[216:217], 0, s[100:101]
	v_lshl_add_u64 v[110:111], v[218:219], 0, s[100:101]
	s_lshl_b64 s[100:101], s[0:1], 6
	v_lshl_add_u64 v[114:115], v[220:221], 0, s[100:101]
	global_load_dwordx4 v[106:109], v[106:107], off
	global_load_dwordx4 v[110:113], v[110:111], off
	global_load_dwordx4 v[114:117], v[114:115], off
.LBB0_531:
	v_pk_add_f32 v[222:223], v[66:67], v[222:223]
	v_pk_add_f32 v[224:225], v[68:69], v[224:225]
	v_pk_add_f32 v[226:227], v[70:71], v[226:227]
	v_pk_add_f32 v[228:229], v[72:73], v[228:229]
	v_pk_add_f32 v[230:231], v[74:75], v[230:231]
	v_pk_add_f32 v[232:233], v[76:77], v[232:233]
	v_pk_add_f32 v[234:235], v[78:79], v[234:235]
	v_pk_add_f32 v[236:237], v[80:81], v[236:237]
	v_pk_add_f32 v[222:223], v[222:223], v[224:225]
	v_pk_add_f32 v[226:227], v[226:227], v[228:229]
	v_pk_add_f32 v[230:231], v[230:231], v[232:233]
	v_pk_add_f32 v[234:235], v[234:235], v[236:237]
	v_pk_add_f32 v[222:223], v[222:223], v[226:227]
	v_pk_add_f32 v[230:231], v[230:231], v[234:235]
	v_pk_add_f32 v[222:223], v[222:223], v[230:231]
	v_add_f32_e32 v222, v222, v223
	v_add_f32_e32 v157, v157, v222
	v_add_u32_e32 v174, s5, v156
	ds_read_b64_tr_b16 v[66:67], v174 offset:0
	ds_read_b64_tr_b16 v[68:69], v174 offset:0x800
	ds_read_b64_tr_b16 v[158:159], v174 offset:0x200
	ds_read_b64_tr_b16 v[160:161], v174 offset:0xa00
	s_waitcnt lgkmcnt(4)
	s_barrier
	s_setprio 2
	ds_read_b64_tr_b16 v[70:71], v174 offset:0x1000
	ds_read_b64_tr_b16 v[72:73], v174 offset:0x1800
	ds_read_b64_tr_b16 v[162:163], v174 offset:0x1200
	ds_read_b64_tr_b16 v[164:165], v174 offset:0x1a00
	ds_read_b64_tr_b16 v[74:75], v174 offset:0x2000
	ds_read_b64_tr_b16 v[76:77], v174 offset:0x2800
	ds_read_b64_tr_b16 v[166:167], v174 offset:0x2200
	ds_read_b64_tr_b16 v[168:169], v174 offset:0x2a00
	ds_read_b64_tr_b16 v[78:79], v174 offset:0x3000
	ds_read_b64_tr_b16 v[80:81], v174 offset:0x3800
	ds_read_b64_tr_b16 v[170:171], v174 offset:0x3200
	ds_read_b64_tr_b16 v[172:173], v174 offset:0x3a00
	s_waitcnt lgkmcnt(14)
	v_mfma_f32_32x32x16_bf16 v[34:49], v[54:57], v[66:69], v[34:49]
	s_waitcnt lgkmcnt(12)
	v_mfma_f32_32x32x16_bf16 v[18:33], v[54:57], v[158:161], v[18:33]
	v_add_u32_e32 v54, s10, v146
	v_add_u32_e32 v55, v54, v147
	s_waitcnt lgkmcnt(10)
	v_mfma_f32_32x32x16_bf16 v[34:49], v[50:53], v[70:73], v[34:49]
	s_waitcnt lgkmcnt(8)
	v_mfma_f32_32x32x16_bf16 v[18:33], v[50:53], v[162:165], v[18:33]
	ds_read_b128 v[50:53], v55 offset:49152
	ds_read_b128 v[158:161], v55 offset:57344
	v_add_u32_e32 v55, v54, v148
	s_waitcnt lgkmcnt(8)
	v_mfma_f32_32x32x16_bf16 v[34:49], v[58:61], v[74:77], v[34:49]
	s_waitcnt lgkmcnt(6)
	v_mfma_f32_32x32x16_bf16 v[18:33], v[58:61], v[166:169], v[18:33]
	ds_read_b128 v[162:165], v55 offset:49152
	ds_read_b128 v[166:169], v55 offset:57344
	v_add_u32_e32 v55, v54, v149
	s_waitcnt lgkmcnt(6)
	v_mfma_f32_32x32x16_bf16 v[34:49], v[62:65], v[78:81], v[34:49]
	s_waitcnt lgkmcnt(4)
	v_mfma_f32_32x32x16_bf16 v[18:33], v[62:65], v[170:173], v[18:33]
	ds_read_b128 v[170:173], v55 offset:49152
	ds_read_b128 v[178:181], v55 offset:57344
	v_add_u32_e32 v55, v54, v150
	ds_read_b128 v[182:185], v55 offset:49152
	ds_read_b128 v[186:189], v55 offset:57344
	v_add_u32_e32 v55, v54, v151
	v_add_u32_e32 v54, v54, v152
	ds_read_b128 v[190:193], v55 offset:49152
	ds_read_b128 v[194:197], v55 offset:57344
	ds_read_b128 v[198:201], v54 offset:49152
	ds_read_b128 v[202:205], v54 offset:57344
	s_waitcnt lgkmcnt(11)
	v_mfma_f32_32x32x16_bf16 v[66:81], v[50:53], v[82:85], v[2:17]
	s_waitcnt lgkmcnt(9)
	v_mfma_f32_32x32x16_bf16 v[66:81], v[162:165], v[86:89], v[66:81]
	s_waitcnt lgkmcnt(7)
	v_mfma_f32_32x32x16_bf16 v[66:81], v[170:173], v[90:93], v[66:81]
	s_waitcnt lgkmcnt(5)
	v_mfma_f32_32x32x16_bf16 v[66:81], v[182:185], v[94:97], v[66:81]
	s_waitcnt lgkmcnt(3)
	v_mfma_f32_32x32x16_bf16 v[66:81], v[190:193], v[98:101], v[66:81]
	s_waitcnt lgkmcnt(1)
	v_mfma_f32_32x32x16_bf16 v[66:81], v[198:201], v[102:105], v[66:81]
	s_waitcnt lgkmcnt(0)
	v_mfma_f32_32x32x16_bf16 v[50:65], v[158:161], v[82:85], v[2:17]
	v_mfma_f32_32x32x16_bf16 v[50:65], v[166:169], v[86:89], v[50:65]
	v_mfma_f32_32x32x16_bf16 v[50:65], v[178:181], v[90:93], v[50:65]
	v_mfma_f32_32x32x16_bf16 v[50:65], v[186:189], v[94:97], v[50:65]
	v_mfma_f32_32x32x16_bf16 v[50:65], v[194:197], v[98:101], v[50:65]
	v_mfma_f32_32x32x16_bf16 v[50:65], v[202:205], v[102:105], v[50:65]
	s_setprio 0
	v_max3_f32 v158, v66, v67, v68
	v_max3_f32 v159, v69, v70, v71
	v_max3_f32 v158, v158, v72, v73
	v_max3_f32 v159, v159, v74, v75
	v_max3_f32 v158, v158, v76, v77
	v_max3_f32 v159, v159, v78, v79
	v_max3_f32 v158, v158, v80, v81
	s_nop 3
	v_max3_f32 v159, v159, v50, v51
	v_max3_f32 v158, v158, v52, v53
	v_max3_f32 v159, v159, v54, v55
	v_max3_f32 v158, v158, v56, v57
	v_max3_f32 v159, v159, v58, v59
	v_max3_f32 v158, v158, v60, v61
	v_max3_f32 v159, v159, v62, v63
	v_max3_f32 v158, v158, v64, v65
	v_max_f32_e32 v159, v158, v159
	v_cmp_ge_f32_e32 vcc, s93, v159
	s_cmp_eq_u64 vcc, exec
	v_mov_b32_e32 v158, 1.0
	s_barrier
	s_cbranch_scc0 .LBB0_541

; #define LAS __attribute__((address_space(3)))
; #define SLOAD(i, t) do { const long k0_ = KROW(t); sg[i].a0 = *(const bf16x8*)(KVh + (k0_ + sr) * 1024 + sc); sg[i].a1 = *(const bf16x8*)(KVh + (k0_ + 32 + sr) * 1024 + sc); \
;     sg[i].rp = *(const bf16x8*)(KR + (k0_ + rr) * 32 + rc); } while (0)
; #define SWRITE_AT(boff, i) do { *(LAS bf16x8*)(lds + (boff) + st0) = sg[i].a0; *(LAS bf16x8*)(lds + (boff) + st1) = sg[i].a1; *(LAS bf16x8*)(lds + (boff) + st2) = sg[i].rp; } while (0)
; __device__ __forceinline__ void attn_unit(const bf16_t* __restrict__ Qb, bool rope_q, int tq0, const bf16_t* __restrict__ KVh, const bf16_t* __restrict__ KR,
;                                           int ctx_row0, int lat_row0, int NT, bf16_t* __restrict__ Ob, LAS unsigned char* lds, int wave_s) {
;     ...
;   const int trail = (wave_s >= 4) ? 1 : 0;
;   const LAS unsigned char* Kb = lds + OFF_K;
;   f32x16 p0, p1; float alpha; bf16x8 pa0, pa1, pa2, pa3;
;   SLOAD(0, 0); SLOAD(1, 1);
;   asm volatile("s_waitcnt vmcnt(3)" ::: "memory"); SWRITE_AT(0, 0);
;   if (trail) { asm volatile("s_waitcnt vmcnt(0)" ::: "memory"); SWRITE_AT(BUFB, 1); SLOAD(1, 2); SLOAD(0, 3); }
;   else { SLOAD(0, 2); }
;   __syncthreads();
;   if (trail) __syncthreads();
;   int bV = 0, bK = 0, bN = BUFB, bNN = 2 * BUFB;
.LBB0_536:
	s_cmpk_gt_u32 s11, 0x81
	s_cselect_b64 s[0:1], -1, 0
	s_and_b64 vcc, exec, s[0:1]
	s_cbranch_vccnz .LBB0_538
	s_add_i32 s23, s23, 2
	s_and_b64 s[24:25], s[54:55], exec
	s_cselect_b32 s24, s5, s22
	v_add_u32_e32 v158, s24, v131
	s_min_u32 s23, s23, 0x81
	s_waitcnt vmcnt(3)
	ds_write_b128 v158, v[118:121]
	v_add_u32_e32 v118, s24, v133
	s_lshl_b32 s23, s23, 6
	ds_write_b128 v118, v[122:125]
	v_add_u32_e32 v118, s24, v145
	s_add_i32 s24, s4, s23
	s_ashr_i32 s25, s24, 31
	ds_write_b128 v118, v[126:129] offset:49152
	s_lshl_b64 s[100:101], s[24:25], 11
	v_lshl_add_u64 v[118:119], v[216:217], 0, s[100:101]
	v_lshl_add_u64 v[122:123], v[218:219], 0, s[100:101]
	s_lshl_b64 s[100:101], s[24:25], 6
	v_lshl_add_u64 v[126:127], v[220:221], 0, s[100:101]
	global_load_dwordx4 v[118:121], v[118:119], off
	global_load_dwordx4 v[122:125], v[122:123], off
	global_load_dwordx4 v[126:129], v[126:127], off

; __device__ __forceinline__ void softmaxT(f32x16& p0, f32x16& p1, float& mref, f32x16& negm, float& l_reg, float& alpha, bf16x8& pa0, bf16x8& pa1, bf16x8& pa2, bf16x8& pa3) {
;     ...
;   { auto rr = __builtin_amdgcn_permlane32_swap(__float_as_uint(pmax), __float_as_uint(pmax), false, false);
;     pmax = __builtin_fmaxf(__uint_as_float(rr[0]), __uint_as_float(rr[1])); }
;   if (__builtin_expect(__all(pmax <= THR2), 1)) { alpha = 1.f; }
;   else { const float dl = __builtin_fmaxf(pmax, 0.f); mref += dl; alpha = __builtin_amdgcn_exp2f(-dl); l_reg *= alpha;
; #pragma unroll
;     for (int r = 0; r < 16; ++r) { p0[r] -= dl; p1[r] -= dl; negm[r] = -mref; }
;     asm volatile("" : "+v"(negm)); }
.LBB0_540:
	v_mov_b32_e32 v158, v159
	s_nop 1
	v_permlane32_swap_b32_e32 v158, v159
	v_max_f32_e32 v159, v158, v159
	v_max_f32_e32 v2, v159, v159
	v_max_f32_e32 v4, 0, v2
	v_exp_f32_e64 v158, -v4
	v_add_f32_e32 v153, v153, v4
	v_xor_b32_e32 v2, 0x80000000, v153
	v_pk_add_f32 v[66:67], v[66:67], v[4:5] op_sel_hi:[1,0] neg_lo:[0,1] neg_hi:[0,1]
	v_mul_f32_e32 v157, v157, v158
	v_pk_add_f32 v[50:51], v[50:51], v[4:5] op_sel_hi:[1,0] neg_lo:[0,1] neg_hi:[0,1]
	v_pk_add_f32 v[68:69], v[68:69], v[4:5] op_sel_hi:[1,0] neg_lo:[0,1] neg_hi:[0,1]
	v_pk_add_f32 v[52:53], v[52:53], v[4:5] op_sel_hi:[1,0] neg_lo:[0,1] neg_hi:[0,1]
	v_pk_add_f32 v[70:71], v[70:71], v[4:5] op_sel_hi:[1,0] neg_lo:[0,1] neg_hi:[0,1]
	v_pk_add_f32 v[54:55], v[54:55], v[4:5] op_sel_hi:[1,0] neg_lo:[0,1] neg_hi:[0,1]
	v_pk_add_f32 v[72:73], v[72:73], v[4:5] op_sel_hi:[1,0] neg_lo:[0,1] neg_hi:[0,1]
	v_pk_add_f32 v[56:57], v[56:57], v[4:5] op_sel_hi:[1,0] neg_lo:[0,1] neg_hi:[0,1]
	v_pk_add_f32 v[74:75], v[74:75], v[4:5] op_sel_hi:[1,0] neg_lo:[0,1] neg_hi:[0,1]
	v_pk_add_f32 v[58:59], v[58:59], v[4:5] op_sel_hi:[1,0] neg_lo:[0,1] neg_hi:[0,1]
	v_pk_add_f32 v[76:77], v[76:77], v[4:5] op_sel_hi:[1,0] neg_lo:[0,1] neg_hi:[0,1]
	v_pk_add_f32 v[60:61], v[60:61], v[4:5] op_sel_hi:[1,0] neg_lo:[0,1] neg_hi:[0,1]
	v_pk_add_f32 v[78:79], v[78:79], v[4:5] op_sel_hi:[1,0] neg_lo:[0,1] neg_hi:[0,1]
	v_pk_add_f32 v[62:63], v[62:63], v[4:5] op_sel_hi:[1,0] neg_lo:[0,1] neg_hi:[0,1]
	v_pk_add_f32 v[80:81], v[80:81], v[4:5] op_sel_hi:[1,0] neg_lo:[0,1] neg_hi:[0,1]
	v_pk_add_f32 v[64:65], v[64:65], v[4:5] op_sel_hi:[1,0] neg_lo:[0,1] neg_hi:[0,1]
	v_mov_b32_e32 v3, v2
	v_mov_b32_e32 v4, v2
	v_mov_b32_e32 v5, v2
	v_mov_b32_e32 v6, v2
	v_mov_b32_e32 v7, v2
	v_mov_b32_e32 v8, v2
	v_mov_b32_e32 v9, v2
	v_mov_b32_e32 v10, v2
	v_mov_b32_e32 v11, v2
	v_mov_b32_e32 v12, v2
	v_mov_b32_e32 v13, v2
	v_mov_b32_e32 v14, v2
	v_mov_b32_e32 v15, v2
	v_mov_b32_e32 v16, v2
	v_mov_b32_e32 v17, v2
	s_branch .LBB0_525
